# attention unit prologue: Q-fragment loads issued right after the unit decode instead of behind the drained key-bias copy
# speedup vs baseline: 1.0397x; 1.0051x over previous
.LBB0_352:
	s_or_b64 exec, exec, s[6:7]
	s_lshr_b32 s6, s88, 4
	s_and_b32 s59, s6, 8
	s_not_b32 s6, s88
	s_lshl_b32 s6, s6, 5
	s_and_b32 s8, s6, 0xf00
	s_add_i32 s6, s8, 0x100
	v_mov_b32_e32 v34, v208
	s_lshr_b32 s60, s6, 6
	s_and_b32 s61, s88, 7
	s_lshr_b32 s10, s88, 8
	s_add_i32 s54, s60, -4
	v_and_b32_e32 v204, 63, v34
	s_or_b32 s58, s59, s61
	v_readfirstlane_b32 s56, v34
	s_mov_b32 s9, s11
	s_lshl_b32 s63, s10, 4
	s_lshl_b64 s[98:99], s[10:11], 12
	s_or_b64 s[98:99], s[98:99], s[8:9]
	s_lshr_b32 s101, s56, 6
	s_lshl_b32 s101, s101, 5
	s_add_u32 s98, s98, s101
	s_addc_u32 s99, s99, 0
	s_lshl_b64 s[98:99], s[98:99], 11
	s_add_u32 s98, s69, s98
	s_addc_u32 s99, s70, s99
	s_lshl_b32 s101, s58, 7
	s_add_u32 s98, s98, s101
	s_addc_u32 s99, s99, 0
	v_and_b32_e32 v112, 31, v34
	v_lshlrev_b32_e32 v112, 11, v112
	v_lshrrev_b32_e32 v113, 5, v204
	v_lshl_or_b32 v112, v113, 4, v112
	global_load_dwordx4 v[124:127], v112, s[98:99]
	global_load_dwordx4 v[120:123], v112, s[98:99] offset:32
	global_load_dwordx4 v[116:119], v112, s[98:99] offset:64
	global_load_dwordx4 v[112:115], v112, s[98:99] offset:96
	v_cmp_gt_u32_e32 vcc, s54, v204
	s_mov_b64 s[52:53], 0
	s_and_saveexec_b64 s[6:7], vcc
	s_cbranch_execz .LBB0_354
	s_or_b32 s52, s58, s63
	s_mov_b32 s53, s11
	s_lshl_b64 s[52:53], s[52:53], 14
	s_add_u32 s52, s77, s52
	s_addc_u32 s53, s78, s53
	s_lshl_b32 s55, s8, 2
	v_lshlrev_b32_e32 v0, 8, v204
	v_mov_b32_e32 v2, s55
	global_load_dword v2, v2, s[52:53]
	s_nop 0
	global_load_dword v0, v0, s[52:53] offset:252
	s_waitcnt vmcnt(0)
	v_sub_f32_e32 v0, v2, v0
	v_cmp_gt_f32_e32 vcc, v0, v201
	s_and_b64 s[52:53], vcc, exec

.LBB0_357:
	s_or_b64 exec, exec, s[6:7]
	s_lshl_b64 s[52:53], s[10:11], 12
	s_or_b64 s[52:53], s[52:53], s[8:9]
	s_lshl_b32 s9, s62, 5
	s_lshl_b32 s6, s58, 6
	s_ashr_i32 s7, s9, 31
	s_add_u32 s52, s52, s9
	s_addc_u32 s53, s53, s7
	s_lshl_b64 s[58:59], s[52:53], 11
	s_add_u32 s7, s69, s58
	v_and_b32_e32 v206, 31, v34
	s_addc_u32 s10, s70, s59
	s_lshl_b32 s63, s6, 1
	v_lshrrev_b32_e32 v207, 5, v204
	s_add_u32 s6, s7, s63
	v_lshlrev_b32_e32 v0, 11, v206
	s_addc_u32 s7, s10, 0
	v_lshl_or_b32 v0, v207, 4, v0
	s_nop 0
	s_nop 0
	s_nop 0
	s_nop 0
	s_cmp_lg_u32 0, -1
	s_cselect_b32 s6, 0, 0
	v_lshlrev_b32_e32 v215, 2, v207
	v_lshlrev_b32_e32 v0, 10, v207
	v_lshlrev_b32_e32 v4, 4, v206
	s_add_i32 s6, s6, s55
	v_lshl_add_u64 v[2:3], v[196:197], 0, s[44:45]
	v_add3_u32 v217, 0, v0, v4
	v_mov_b32_e32 v0, v215
	s_addk_i32 s6, 0x4000
	s_mov_b32 s7, m0
	s_mov_b32 m0, s6
	s_nop 0
	global_load_lds_dwordx4 v[2:3], off
	s_mov_b32 m0, s7
	s_waitcnt vmcnt(3) lgkmcnt(0)
	s_barrier
	ds_read_b128 v[18:21], v217
	v_lshl_add_u32 v0, v0, 2, 0
	v_add_u32_e32 v0, 0x14800, v0
	ds_read_b128 v[2:5], v0
	ds_read_b128 v[6:9], v0 offset:32
	ds_read_b128 v[10:13], v0 offset:64
	ds_read_b128 v[14:17], v0 offset:96
	ds_read_b128 v[36:39], v217 offset:512
	v_or_b32_e32 v216, s9, v206
	s_cmp_lt_i32 s66, 5
	s_waitcnt vmcnt(3) lgkmcnt(1)
	v_mfma_f32_32x32x16_bf16 v[2:17], v[18:21], v[124:127], v[2:17]
	ds_read_b128 v[18:21], v0 offset:128
	ds_read_b128 v[22:25], v0 offset:160
	ds_read_b128 v[26:29], v0 offset:192
	ds_read_b128 v[30:33], v0 offset:224
	s_waitcnt lgkmcnt(0)
	v_mfma_f32_32x32x16_bf16 v[18:33], v[36:39], v[124:127], v[18:33]
	ds_read_b128 v[36:39], v217 offset:2048
	ds_read_b128 v[40:43], v217 offset:2560
	s_waitcnt vmcnt(2) lgkmcnt(1)
	v_mfma_f32_32x32x16_bf16 v[2:17], v[36:39], v[120:123], v[2:17]
	s_waitcnt lgkmcnt(0)
	v_mfma_f32_32x32x16_bf16 v[18:33], v[40:43], v[120:123], v[18:33]
	ds_read_b128 v[36:39], v217 offset:4096
	ds_read_b128 v[40:43], v217 offset:4608
	s_waitcnt vmcnt(1) lgkmcnt(1)
	v_mfma_f32_32x32x16_bf16 v[2:17], v[36:39], v[116:119], v[2:17]
	s_waitcnt lgkmcnt(0)
	v_mfma_f32_32x32x16_bf16 v[18:33], v[40:43], v[116:119], v[18:33]
	ds_read_b128 v[36:39], v217 offset:6144
	ds_read_b128 v[40:43], v217 offset:6656
	s_waitcnt vmcnt(0) lgkmcnt(1)
	v_mfma_f32_32x32x16_bf16 v[2:17], v[36:39], v[112:115], v[2:17]
	s_waitcnt lgkmcnt(0)
	v_mfma_f32_32x32x16_bf16 v[18:33], v[40:43], v[112:115], v[18:33]
	s_nop 15
	s_nop 7
	s_cbranch_scc0 .LBB0_359
	v_subrev_u32_e32 v0, s57, v215
	v_add_u32_e32 v36, 0x120, v0
	v_add_u32_e32 v35, 0x100, v0
	v_cmp_le_i32_e32 vcc, v36, v216
	s_nop 6
	v_cndmask_b32_e32 v18, v202, v18, vcc
	v_cmp_lt_i32_e32 vcc, v35, v216
	s_nop 1
	v_cndmask_b32_e32 v3, v202, v3, vcc
	v_cmp_le_i32_e32 vcc, v35, v216
	v_add_u32_e32 v35, 0x121, v0
	s_nop 0
	v_cndmask_b32_e32 v2, v202, v2, vcc
	v_cmp_le_i32_e32 vcc, v35, v216
	v_add_u32_e32 v35, 0x102, v0
	s_nop 0
	v_cndmask_b32_e32 v19, v202, v19, vcc
	v_cmp_le_i32_e32 vcc, v35, v216
	v_add_u32_e32 v35, 0x122, v0
	s_nop 0
	v_cndmask_b32_e32 v4, v202, v4, vcc
	v_cmp_le_i32_e32 vcc, v35, v216
	v_add_u32_e32 v35, 0x103, v0
	s_nop 0
	v_cndmask_b32_e32 v20, v202, v20, vcc
	v_cmp_le_i32_e32 vcc, v35, v216
	v_add_u32_e32 v35, 0x123, v0
	s_nop 0
	v_cndmask_b32_e32 v5, v202, v5, vcc
	v_cmp_le_i32_e32 vcc, v35, v216
	v_add_u32_e32 v35, 0x108, v0
	s_nop 0
	v_cndmask_b32_e32 v21, v202, v21, vcc
	v_cmp_le_i32_e32 vcc, v35, v216
	v_add_u32_e32 v35, 0x128, v0
	s_nop 0
	v_cndmask_b32_e32 v6, v202, v6, vcc
	v_cmp_le_i32_e32 vcc, v35, v216
	v_add_u32_e32 v35, 0x109, v0
	s_nop 0
	v_cndmask_b32_e32 v22, v202, v22, vcc
	v_cmp_le_i32_e32 vcc, v35, v216
	v_add_u32_e32 v35, 0x129, v0
	s_nop 0
	v_cndmask_b32_e32 v7, v202, v7, vcc
	v_cmp_le_i32_e32 vcc, v35, v216
	v_add_u32_e32 v35, 0x10a, v0
	s_nop 0
	v_cndmask_b32_e32 v23, v202, v23, vcc
	v_cmp_le_i32_e32 vcc, v35, v216
	v_add_u32_e32 v35, 0x12a, v0
	s_nop 0
	v_cndmask_b32_e32 v8, v202, v8, vcc
	v_cmp_le_i32_e32 vcc, v35, v216
	v_add_u32_e32 v35, 0x10b, v0
	s_nop 0
	v_cndmask_b32_e32 v24, v202, v24, vcc
	v_cmp_le_i32_e32 vcc, v35, v216
	v_add_u32_e32 v35, 0x12b, v0
	s_nop 0
	v_cndmask_b32_e32 v9, v202, v9, vcc
	v_cmp_le_i32_e32 vcc, v35, v216
	v_add_u32_e32 v35, 0x110, v0
	s_nop 0
	v_cndmask_b32_e32 v25, v202, v25, vcc
	v_cmp_le_i32_e32 vcc, v35, v216
	v_add_u32_e32 v35, 0x130, v0
	s_nop 0
	v_cndmask_b32_e32 v10, v202, v10, vcc
	v_cmp_le_i32_e32 vcc, v35, v216
	v_add_u32_e32 v35, 0x111, v0
	s_nop 0
	v_cndmask_b32_e32 v26, v202, v26, vcc
	v_cmp_le_i32_e32 vcc, v35, v216
	v_add_u32_e32 v35, 0x131, v0
	s_nop 0
	v_cndmask_b32_e32 v11, v202, v11, vcc
	v_cmp_le_i32_e32 vcc, v35, v216
	v_add_u32_e32 v35, 0x112, v0
	s_nop 0
	v_cndmask_b32_e32 v27, v202, v27, vcc
	v_cmp_le_i32_e32 vcc, v35, v216
	v_add_u32_e32 v35, 0x132, v0
	s_nop 0
	v_cndmask_b32_e32 v12, v202, v12, vcc
	v_cmp_le_i32_e32 vcc, v35, v216
	v_add_u32_e32 v35, 0x113, v0
	s_nop 0
	v_cndmask_b32_e32 v28, v202, v28, vcc
	v_cmp_le_i32_e32 vcc, v35, v216
	v_add_u32_e32 v35, 0x133, v0
	s_nop 0
	v_cndmask_b32_e32 v13, v202, v13, vcc
	v_cmp_le_i32_e32 vcc, v35, v216
	v_add_u32_e32 v35, 0x118, v0
	s_nop 0
	v_cndmask_b32_e32 v29, v202, v29, vcc
	v_cmp_le_i32_e32 vcc, v35, v216
	v_add_u32_e32 v35, 0x138, v0
	s_nop 0
	v_cndmask_b32_e32 v14, v202, v14, vcc
	v_cmp_le_i32_e32 vcc, v35, v216
	v_add_u32_e32 v35, 0x119, v0
	s_nop 0
	v_cndmask_b32_e32 v30, v202, v30, vcc
	v_cmp_le_i32_e32 vcc, v35, v216
	v_add_u32_e32 v35, 0x139, v0
	s_nop 0
	v_cndmask_b32_e32 v15, v202, v15, vcc
	v_cmp_le_i32_e32 vcc, v35, v216
	v_add_u32_e32 v35, 0x11a, v0
	s_nop 0
	v_cndmask_b32_e32 v31, v202, v31, vcc
	v_cmp_le_i32_e32 vcc, v35, v216
	v_add_u32_e32 v35, 0x13a, v0
	s_nop 0
	v_cndmask_b32_e32 v16, v202, v16, vcc
	v_cmp_le_i32_e32 vcc, v35, v216
	v_add_u32_e32 v35, 0x11b, v0
	v_add_u32_e32 v0, 0x13b, v0
	v_cndmask_b32_e32 v32, v202, v32, vcc
	v_cmp_le_i32_e32 vcc, v35, v216
	s_nop 1
	v_cndmask_b32_e32 v17, v202, v17, vcc
	v_cmp_le_i32_e32 vcc, v0, v216
	s_nop 1
	v_cndmask_b32_e32 v33, v202, v33, vcc
